# G4 last-layer delayed start for the 16-unit workgroups, shorter delay (6 x s_sleep 127) for margin against the slack limit
# baseline (speedup 1.0000x reference)
.LBB0_1142:
	s_or_b64 exec, exec, s[0:1]
	v_readlane_b32 s4, v252, 4
	s_mov_b64 s[0:1], 0
	v_readlane_b32 s18, v252, 18
	s_waitcnt lgkmcnt(0)
	s_barrier
	v_readlane_b32 s19, v252, 19
	s_add_u32 s58, s18, s0
	s_addc_u32 s59, s19, s1
	s_add_u32 s56, s58, 0x6a00000
	v_mov_b32_e32 v1, v0
	v_readlane_b32 s33, v252, 0
	v_readlane_b32 s61, v252, 3
	s_addc_u32 s57, s59, 0
	s_cmpk_eq_i32 s61, 0x100
	s_cselect_b64 s[2:3], -1, 0
	s_cmpk_lg_i32 s61, 0x100
	v_mov_b32_e32 v10, v0
	v_readfirstlane_b32 s60, v1
	s_cselect_b64 s[22:23], -1, 0
	s_cmpk_lt_i32 s33, 0x80
	s_cbranch_scc1 .Lg4_nodelay
	v_readlane_b32 s24, v254, 46
	s_nop 0
	s_cmp_lg_u32 s24, 0
	s_cbranch_scc1 .Lg4_nodelay
	s_movk_i32 s24, 6
